# stagger: half of the blocks enter gres1/gres2 ~11us later so epilogue HBM traffic overlaps the other half's k-loops
# speedup vs baseline: 1.0001x; 1.0001x over previous
.LBB0_879:
	s_or_b64 exec, exec, s[0:1]
	s_add_u32 s28, s56, 0x1c000000
	s_addc_u32 s29, s57, 0
	s_add_u32 s0, s56, 0x900000
	s_addc_u32 s1, s57, 0
	s_cmpk_lt_u32 s12, 0x800
	s_mov_b64 s[2:3], s[28:29]
	v_mov_b32_e32 v0, v196
	s_cselect_b64 s[24:25], -1, 0
	s_cmpk_gt_u32 s12, 0x7ff
	s_waitcnt lgkmcnt(0)
	s_barrier
	s_cbranch_scc1 .LBB0_892
	s_lshr_b32 s98, s12, 3
	s_lshr_b32 s99, s12, 8
	s_xor_b32 s98, s98, s99
	s_bitcmp1_b32 s98, 0
	s_cbranch_scc0 .Lstg_gres1_skip
	s_mov_b32 s98, 3
.Lstg_gres1_loop:
	s_sleep 127
	s_sub_u32 s98, s98, 1
	s_cmp_lg_u32 s98, 0
	s_cbranch_scc1 .Lstg_gres1_loop
.Lstg_gres1_skip:
	s_lshr_b32 s4, s12, 6
	s_and_b32 s4, s4, 24
	s_bfe_u32 s5, s12, 0x30003
	s_or_b32 s4, s4, s5
	s_or_b32 s8, s4, s96
	v_mov_b32_e32 v1, v196
	s_lshl_b32 s10, s8, 7
	s_bfe_u32 s9, s12, 0x30006
	v_ashrrev_i32_e32 v4, 3, v1
	v_add_u32_e32 v2, s10, v4
	s_lshl_b32 s11, s9, 7
	v_ashrrev_i32_e32 v3, 31, v2
	v_lshlrev_b64 v[2:3], 11, v[2:3]
	v_lshlrev_b32_e32 v1, 4, v1
	v_add_u32_e32 v4, s11, v4
	v_lshl_add_u64 v[2:3], s[2:3], 0, v[2:3]
	v_and_b32_e32 v128, 0x70, v1
	v_mov_b32_e32 v129, 0
	v_ashrrev_i32_e32 v5, 31, v4
	v_lshl_add_u64 v[2:3], v[2:3], 0, v[128:129]
	v_lshlrev_b64 v[4:5], 11, v[4:5]
	s_mov_b32 s14, 0x10000
	v_lshl_add_u64 v[4:5], s[0:1], 0, v[4:5]
	v_add_co_u32_e32 v6, vcc, s14, v2
	v_lshl_add_u64 v[4:5], v[4:5], 0, v[128:129]
	s_nop 0
	v_addc_co_u32_e32 v7, vcc, 0, v3, vcc
	v_add_co_u32_e32 v8, vcc, s14, v4
	s_mov_b32 s15, 0x20000
	s_nop 0
	v_addc_co_u32_e32 v9, vcc, 0, v5, vcc
	v_add_co_u32_e32 v10, vcc, s15, v2
	s_mov_b32 s4, 0x30000
	s_nop 0
	v_addc_co_u32_e32 v11, vcc, 0, v3, vcc
	v_add_co_u32_e32 v12, vcc, s15, v4
	v_ashrrev_i32_e32 v1, 1, v0
	s_nop 0
	v_addc_co_u32_e32 v13, vcc, 0, v5, vcc
	v_add_co_u32_e32 v14, vcc, s4, v2
	v_and_b32_e32 v138, 0xffffffc0, v1
	s_nop 0
	v_addc_co_u32_e32 v15, vcc, 0, v3, vcc
	v_add_co_u32_e32 v16, vcc, s4, v4
	v_lshrrev_b32_e32 v1, 3, v0
	s_nop 0
	v_addc_co_u32_e32 v17, vcc, 0, v5, vcc
	global_load_dwordx4 v[64:67], v[2:3], off
	global_load_dwordx4 v[68:71], v[2:3], off offset:128
	global_load_dwordx4 v[72:75], v[4:5], off
	global_load_dwordx4 v[76:79], v[4:5], off offset:128
	global_load_dwordx4 v[80:83], v[6:7], off
	global_load_dwordx4 v[84:87], v[6:7], off offset:128
	global_load_dwordx4 v[88:91], v[8:9], off
	global_load_dwordx4 v[92:95], v[8:9], off offset:128
	global_load_dwordx4 v[96:99], v[10:11], off
	global_load_dwordx4 v[100:103], v[10:11], off offset:128
	global_load_dwordx4 v[104:107], v[12:13], off
	global_load_dwordx4 v[108:111], v[12:13], off offset:128
	global_load_dwordx4 v[112:115], v[14:15], off
	global_load_dwordx4 v[116:119], v[14:15], off offset:128
	global_load_dwordx4 v[120:123], v[16:17], off
	global_load_dwordx4 v[124:127], v[16:17], off offset:128
	s_movk_i32 s33, 0x70
	v_and_b32_e32 v139, 4, v1
	v_and_b32_e32 v140, 0x5f, v0
	s_mov_b32 s35, 0x1ffffc0
	s_mov_b64 s[4:5], 0x100
	s_mov_b32 s36, s95
	s_branch .LBB0_882

.LBB0_1501:
	s_or_b64 exec, exec, s[0:1]
	s_add_u32 s0, s56, 0x1300000
	s_addc_u32 s1, s57, 0
	v_mov_b32_e32 v0, v196
	s_andn2_b64 vcc, exec, s[24:25]
	s_waitcnt lgkmcnt(0)
	s_barrier
	s_cbranch_vccnz .LBB0_1514
	s_lshr_b32 s98, s12, 3
	s_lshr_b32 s99, s12, 8
	s_xor_b32 s98, s98, s99
	s_bitcmp1_b32 s98, 0
	s_cbranch_scc0 .Lstg_gres2_skip
	s_mov_b32 s98, 3

.Lstg_gres2_skip:
	s_lshr_b32 s2, s12, 6
	s_and_b32 s2, s2, 24
	s_bfe_u32 s3, s12, 0x30003
	s_or_b32 s2, s2, s3
	s_or_b32 s6, s2, s96
	v_mov_b32_e32 v1, v196
	s_lshl_b32 s8, s6, 7
	s_bfe_u32 s7, s12, 0x30006
	v_ashrrev_i32_e32 v4, 3, v1
	v_add_u32_e32 v2, s8, v4
	s_lshl_b32 s9, s7, 7
	v_ashrrev_i32_e32 v3, 31, v2
	v_lshlrev_b64 v[2:3], 11, v[2:3]
	v_lshlrev_b32_e32 v1, 4, v1
	v_add_u32_e32 v4, s9, v4
	v_lshl_add_u64 v[2:3], s[18:19], 0, v[2:3]
	v_and_b32_e32 v128, 0x70, v1
	v_mov_b32_e32 v129, 0
	v_ashrrev_i32_e32 v5, 31, v4
	v_lshl_add_u64 v[2:3], v[2:3], 0, v[128:129]
	v_lshlrev_b64 v[4:5], 11, v[4:5]
	s_mov_b32 s10, 0x10000
	v_lshl_add_u64 v[4:5], s[0:1], 0, v[4:5]
	v_add_co_u32_e32 v6, vcc, s10, v2
	v_lshl_add_u64 v[4:5], v[4:5], 0, v[128:129]
	s_nop 0
	v_addc_co_u32_e32 v7, vcc, 0, v3, vcc
	v_add_co_u32_e32 v8, vcc, s10, v4
	s_mov_b32 s11, 0x20000
	s_nop 0
	v_addc_co_u32_e32 v9, vcc, 0, v5, vcc
	v_add_co_u32_e32 v10, vcc, s11, v2
	s_mov_b32 s2, 0x30000
	s_nop 0
	v_addc_co_u32_e32 v11, vcc, 0, v3, vcc
	v_add_co_u32_e32 v12, vcc, s11, v4
	v_ashrrev_i32_e32 v1, 1, v0
	s_nop 0
	v_addc_co_u32_e32 v13, vcc, 0, v5, vcc
	v_add_co_u32_e32 v14, vcc, s2, v2
	v_and_b32_e32 v166, 0xffffffc0, v1
	s_nop 0
	v_addc_co_u32_e32 v15, vcc, 0, v3, vcc
	v_add_co_u32_e32 v16, vcc, s2, v4
	v_lshrrev_b32_e32 v1, 3, v0
	s_nop 0
	v_addc_co_u32_e32 v17, vcc, 0, v5, vcc
	s_waitcnt vmcnt(0)
	global_load_dwordx4 v[64:67], v[2:3], off
	global_load_dwordx4 v[68:71], v[2:3], off offset:128
	global_load_dwordx4 v[72:75], v[4:5], off
	global_load_dwordx4 v[76:79], v[4:5], off offset:128
	global_load_dwordx4 v[80:83], v[6:7], off
	global_load_dwordx4 v[84:87], v[6:7], off offset:128
	global_load_dwordx4 v[88:91], v[8:9], off
	global_load_dwordx4 v[92:95], v[8:9], off offset:128
	global_load_dwordx4 v[96:99], v[10:11], off
	global_load_dwordx4 v[100:103], v[10:11], off offset:128
	global_load_dwordx4 v[104:107], v[12:13], off
	global_load_dwordx4 v[108:111], v[12:13], off offset:128
	global_load_dwordx4 v[112:115], v[14:15], off
	global_load_dwordx4 v[116:119], v[14:15], off offset:128
	global_load_dwordx4 v[120:123], v[16:17], off
	global_load_dwordx4 v[124:127], v[16:17], off offset:128
	s_movk_i32 s12, 0x70
	v_and_b32_e32 v167, 4, v1
	v_and_b32_e32 v168, 0x5f, v0
	s_mov_b32 s13, 0x1ffffc0
	s_mov_b64 s[2:3], 0x100
	s_branch .LBB0_1504

	.amdhsa_kernel _Z8yoco_fwd6Params
		.amdhsa_group_segment_fixed_size 16
		.amdhsa_private_segment_fixed_size 0
		.amdhsa_kernarg_size 440
		.amdhsa_user_sgpr_count 2
		.amdhsa_user_sgpr_dispatch_ptr 0
		.amdhsa_user_sgpr_queue_ptr 0
		.amdhsa_user_sgpr_kernarg_segment_ptr 1
		.amdhsa_user_sgpr_dispatch_id 0
		.amdhsa_user_sgpr_kernarg_preload_length 0
		.amdhsa_user_sgpr_kernarg_preload_offset 0
		.amdhsa_user_sgpr_private_segment_size 0
		.amdhsa_uses_dynamic_stack 0
		.amdhsa_enable_private_segment 0
		.amdhsa_system_sgpr_workgroup_id_x 1
		.amdhsa_system_sgpr_workgroup_id_y 0
		.amdhsa_system_sgpr_workgroup_id_z 0
		.amdhsa_system_sgpr_workgroup_info 0
		.amdhsa_system_vgpr_workitem_id 2
		.amdhsa_next_free_vgpr 256
		.amdhsa_next_free_sgpr 102
		.amdhsa_accum_offset 256
		.amdhsa_reserve_vcc 1
		.amdhsa_float_round_mode_32 0
		.amdhsa_float_round_mode_16_64 0
		.amdhsa_float_denorm_mode_32 3
		.amdhsa_float_denorm_mode_16_64 3
		.amdhsa_dx10_clamp 1
		.amdhsa_ieee_mode 1
		.amdhsa_fp16_overflow 0
		.amdhsa_tg_split 0
		.amdhsa_exception_fp_ieee_invalid_op 0
		.amdhsa_exception_fp_denorm_src 0
		.amdhsa_exception_fp_ieee_div_zero 0
		.amdhsa_exception_fp_ieee_overflow 0
		.amdhsa_exception_fp_ieee_underflow 0
		.amdhsa_exception_fp_ieee_inexact 0
		.amdhsa_exception_int_div_zero 0
	.end_amdhsa_kernel

amdhsa.kernels:
  - .agpr_count:     0
    .args:
      - .offset:         0
        .size:           184
        .value_kind:     by_value
      - .offset:         184
        .size:           4
        .value_kind:     hidden_block_count_x
      - .offset:         188
        .size:           4
        .value_kind:     hidden_block_count_y
      - .offset:         192
        .size:           4
        .value_kind:     hidden_block_count_z
      - .offset:         196
        .size:           2
        .value_kind:     hidden_group_size_x
      - .offset:         198
        .size:           2
        .value_kind:     hidden_group_size_y
      - .offset:         200
        .size:           2
        .value_kind:     hidden_group_size_z
      - .offset:         202
        .size:           2
        .value_kind:     hidden_remainder_x
      - .offset:         204
        .size:           2
        .value_kind:     hidden_remainder_y
      - .offset:         206
        .size:           2
        .value_kind:     hidden_remainder_z
      - .offset:         224
        .size:           8
        .value_kind:     hidden_global_offset_x
      - .offset:         232
        .size:           8
        .value_kind:     hidden_global_offset_y
      - .offset:         240
        .size:           8
        .value_kind:     hidden_global_offset_z
      - .offset:         248
        .size:           2
        .value_kind:     hidden_grid_dims
      - .offset:         272
        .size:           8
        .value_kind:     hidden_multigrid_sync_arg
      - .offset:         304
        .size:           4
        .value_kind:     hidden_dynamic_lds_size
    .group_segment_fixed_size: 16
    .kernarg_segment_align: 8
    .kernarg_segment_size: 440
    .language:       OpenCL C
    .language_version:
      - 2
      - 0
    .max_flat_workgroup_size: 256
    .name:           _Z8yoco_fwd6Params
    .private_segment_fixed_size: 0
    .sgpr_count:     108
    .sgpr_spill_count: 10
    .symbol:         _Z8yoco_fwd6Params.kd
    .uniform_work_group_size: 1
    .uses_dynamic_stack: false
    .vgpr_count:     256
    .vgpr_spill_count: 0
    .wavefront_size: 64
